# P3 helper waves touch the out-GEMM's first x tile on idle steps (cache prefetch for the P4 epilogue)
# speedup vs baseline: 1.0015x; 1.0015x over previous
; __device__ __forceinline__ unsigned pk2(float lo, float hi) { return f2bf(lo) | (f2bf(hi) << 16); }
; __device__ __forceinline__ size_t blk_off(int row, int col, int K) { return ((size_t)((row >> 8) * (K >> 6) + (col >> 6)) << 14) + (size_t)(((row & 255) << 6) + (col & 63)); }
; #define POOL_ADD(sgn, VV) do { S[0] += sgn bflo((VV).x); S[1] += sgn bfhi((VV).x); S[2] += sgn bflo((VV).y); S[3] += sgn bfhi((VV).y); S[4] += sgn bflo((VV).z); S[5] += sgn bfhi((VV).z); S[6] += sgn bflo((VV).w); S[7] += sgn bfhi((VV).w); } while (0)
; template <int HW> __device__ __forceinline__ void pool_group(const bf16* PROJ, bf16* CAT, int pbase, int T, int t0, int ch) {
;     ...
;     for (int i = 0; i < NL; ++i) { const int s = t0 - HW + i; const v4u z = {0u, 0u, 0u, 0u}; x[i] = (s >= 0 && s < T) ? *(const v4u*)(PROJ + (size_t)(pbase + s) * INW + 3 * ATTW + 8 * ch) : z; }
;     float S[8];
; #pragma unroll
;     for (int c = 0; c < 8; ++c) S[c] = 0.f;
;     ...
; #pragma unroll
;     for (int i = 0; i < 2 * HW; ++i) POOL_ADD(+, x[i]);
; #pragma unroll
;     for (int k = 0; k < 4; ++k) {
;         if (k > 0) { POOL_ADD(-, x[k - 1]); POOL_ADD(+, x[k - 1 + 2 * HW]); }
;         const int t = t0 + k; const float ic = 1.0f / (float)(min(t + HW, T) - max(t - HW, 0)); const v4u w = x[HW + k];
;         v4u ow; ow.x = pk2(S[0] * ic - bflo(w.x), S[1] * ic - bfhi(w.x)); ow.y = pk2(S[2] * ic - bflo(w.y), S[3] * ic - bfhi(w.y));
;         ow.z = pk2(S[4] * ic - bflo(w.z), S[5] * ic - bfhi(w.z)); ow.w = pk2(S[6] * ic - bflo(w.w), S[7] * ic - bfhi(w.w));
;         *(v4u*)(CAT + blk_off(pbase + t, ATTW + 8 * ch, D)) = ow;
.LBB0_355:
	s_or_b64 exec, exec, s[70:71]
	s_waitcnt vmcnt(0)
	v_lshlrev_b32_e32 v166, 16, v82
	v_and_b32_e32 v164, 0xffff0000, v82
	v_lshlrev_b32_e32 v162, 16, v84
	v_and_b32_e32 v160, 0xffff0000, v84
	v_lshlrev_b32_e32 v84, 16, v94
	v_and_b32_e32 v82, 0xffff0000, v94
	v_min_u32_e32 v2, s28, v2
	v_sub_u32_e64 v94, v196, 8 clamp
	v_sub_u32_e32 v2, v2, v94
	v_cvt_f32_i32_e32 v2, v2
	v_lshlrev_b32_e32 v167, 16, v83
	v_and_b32_e32 v165, 0xffff0000, v83
	v_lshlrev_b32_e32 v163, 16, v85
	v_div_scale_f32 v94, s[70:71], v2, v2, 1.0
	v_and_b32_e32 v161, 0xffff0000, v85
	v_lshlrev_b32_e32 v85, 16, v95
	v_and_b32_e32 v83, 0xffff0000, v95
	v_rcp_f32_e32 v95, v94
	v_lshlrev_b32_e32 v158, 16, v58
	v_and_b32_e32 v156, 0xffff0000, v58
	v_lshlrev_b32_e32 v154, 16, v60
	v_and_b32_e32 v152, 0xffff0000, v60
	v_lshlrev_b32_e32 v60, 16, v96
	v_and_b32_e32 v58, 0xffff0000, v96
	v_fma_f32 v96, -v94, v95, 1.0
	v_fmac_f32_e32 v95, v96, v95
	v_div_scale_f32 v96, vcc, 1.0, v2, 1.0
	v_lshlrev_b32_e32 v159, 16, v59
	v_and_b32_e32 v157, 0xffff0000, v59
	v_lshlrev_b32_e32 v155, 16, v61
	v_and_b32_e32 v153, 0xffff0000, v61
	v_lshlrev_b32_e32 v61, 16, v97
	v_and_b32_e32 v59, 0xffff0000, v97
	v_mul_f32_e32 v97, v96, v95
	v_fma_f32 v199, -v94, v97, v96
	v_fmac_f32_e32 v97, v199, v95
	v_fma_f32 v94, -v94, v97, v96
	v_pk_add_f32 v[200:201], v[166:167], 0 op_sel_hi:[1,0]
	v_div_fmas_f32 v94, v94, v95, v97
	v_pk_add_f32 v[202:203], v[164:165], 0 op_sel_hi:[1,0]
	v_div_fixup_f32 v2, v94, v2, 1.0
	v_pk_add_f32 v[94:95], v[200:201], v[158:159]
	v_lshlrev_b32_e32 v97, 16, v35
	v_pk_add_f32 v[94:95], v[94:95], v[84:85]
	v_lshlrev_b32_e32 v96, 16, v34
	v_pk_add_f32 v[202:203], v[202:203], v[156:157]
	v_pk_add_f32 v[94:95], v[94:95], v[96:97]
	v_lshlrev_b32_e32 v97, 16, v43
	v_lshlrev_b32_e32 v96, 16, v42
	v_pk_add_f32 v[202:203], v[202:203], v[82:83]
	v_and_b32_e32 v35, 0xffff0000, v35
	v_and_b32_e32 v34, 0xffff0000, v34
	v_pk_add_f32 v[94:95], v[94:95], v[96:97]
	v_lshlrev_b32_e32 v97, 16, v39
	v_lshlrev_b32_e32 v96, 16, v38
	v_pk_add_f32 v[34:35], v[202:203], v[34:35]
	v_and_b32_e32 v43, 0xffff0000, v43
	v_and_b32_e32 v42, 0xffff0000, v42
	v_pk_add_f32 v[94:95], v[94:95], v[96:97]
	v_lshlrev_b32_e32 v97, 16, v51
	v_lshlrev_b32_e32 v96, 16, v50
	v_pk_add_f32 v[34:35], v[34:35], v[42:43]
	v_and_b32_e32 v39, 0xffff0000, v39
	v_and_b32_e32 v38, 0xffff0000, v38
	v_pk_add_f32 v[94:95], v[94:95], v[96:97]
	v_lshlrev_b32_e32 v97, 16, v47
	v_lshlrev_b32_e32 v96, 16, v46
	v_pk_add_f32 v[34:35], v[34:35], v[38:39]
	v_and_b32_e32 v39, 0xffff0000, v51
	v_and_b32_e32 v38, 0xffff0000, v50
	v_lshlrev_b32_e32 v217, 16, v103
	v_lshlrev_b32_e32 v216, 16, v102
	v_pk_add_f32 v[200:201], v[94:95], v[96:97]
	v_pk_add_f32 v[34:35], v[34:35], v[38:39]
	v_and_b32_e32 v39, 0xffff0000, v47
	v_and_b32_e32 v38, 0xffff0000, v46
	v_and_b32_e32 v219, 0xffff0000, v103
	v_and_b32_e32 v218, 0xffff0000, v102
	v_lshlrev_b32_e32 v103, 16, v55
	v_lshlrev_b32_e32 v102, 16, v54
	v_pk_add_f32 v[200:201], v[200:201], v[216:217]
	v_pk_add_f32 v[38:39], v[34:35], v[38:39]
	v_lshlrev_b32_e32 v97, 16, v99
	v_lshlrev_b32_e32 v96, 16, v98
	v_pk_add_f32 v[200:201], v[200:201], v[102:103]
	v_and_b32_e32 v51, 0xffff0000, v55
	v_and_b32_e32 v50, 0xffff0000, v54
	v_pk_add_f32 v[38:39], v[38:39], v[218:219]
	v_lshlrev_b32_e32 v95, 16, v91
	v_lshlrev_b32_e32 v94, 16, v90
	v_pk_add_f32 v[200:201], v[200:201], v[96:97]
	v_and_b32_e32 v43, 0xffff0000, v99
	v_and_b32_e32 v42, 0xffff0000, v98
	v_pk_add_f32 v[38:39], v[38:39], v[50:51]
	v_lshlrev_b32_e32 v209, 16, v123
	v_lshlrev_b32_e32 v208, 16, v122
	v_pk_add_f32 v[200:201], v[200:201], v[94:95]
	v_and_b32_e32 v35, 0xffff0000, v91
	v_and_b32_e32 v34, 0xffff0000, v90
	v_pk_add_f32 v[38:39], v[38:39], v[42:43]
	v_and_b32_e32 v211, 0xffff0000, v123
	v_and_b32_e32 v210, 0xffff0000, v122
	v_lshlrev_b32_e32 v212, 16, v118
	v_lshlrev_b32_e32 v213, 16, v119
	v_pk_add_f32 v[38:39], v[38:39], v[34:35]
	v_pk_add_f32 v[46:47], v[200:201], v[208:209]
	v_and_b32_e32 v118, 0xffff0000, v118
	v_and_b32_e32 v119, 0xffff0000, v119
	v_pk_add_f32 v[38:39], v[38:39], v[210:211]
	v_pk_add_f32 v[46:47], v[46:47], v[212:213]
	v_lshlrev_b32_e32 v55, 16, v115
	v_lshlrev_b32_e32 v54, 16, v114
	v_pk_add_f32 v[38:39], v[38:39], v[118:119]
	v_pk_add_f32 v[46:47], v[46:47], v[54:55]
	v_and_b32_e32 v55, 0xffff0000, v115
	v_and_b32_e32 v54, 0xffff0000, v114
	v_pk_add_f32 v[38:39], v[38:39], v[54:55]
	v_lshlrev_b32_e32 v55, 16, v111
	v_lshlrev_b32_e32 v54, 16, v110
	v_pk_add_f32 v[204:205], v[162:163], 0 op_sel_hi:[1,0]
	v_pk_add_f32 v[90:91], v[46:47], v[54:55]
	v_and_b32_e32 v47, 0xffff0000, v111
	v_and_b32_e32 v46, 0xffff0000, v110
	v_pk_add_f32 v[206:207], v[160:161], 0 op_sel_hi:[1,0]
	v_pk_add_f32 v[98:99], v[38:39], v[46:47]
	v_pk_add_f32 v[38:39], v[204:205], v[154:155]
	v_lshlrev_b32_e32 v47, 16, v37
	v_pk_add_f32 v[38:39], v[38:39], v[60:61]
	v_lshlrev_b32_e32 v46, 16, v36
	v_pk_add_f32 v[202:203], v[206:207], v[152:153]
	v_pk_add_f32 v[38:39], v[38:39], v[46:47]
	v_lshlrev_b32_e32 v47, 16, v45
	v_lshlrev_b32_e32 v46, 16, v44
	v_pk_add_f32 v[202:203], v[202:203], v[58:59]
	v_and_b32_e32 v37, 0xffff0000, v37
	v_and_b32_e32 v36, 0xffff0000, v36
	v_pk_add_f32 v[38:39], v[38:39], v[46:47]
	v_lshlrev_b32_e32 v47, 16, v41
	v_lshlrev_b32_e32 v46, 16, v40
	v_pk_add_f32 v[36:37], v[202:203], v[36:37]
	v_and_b32_e32 v45, 0xffff0000, v45
	v_and_b32_e32 v44, 0xffff0000, v44
	v_pk_add_f32 v[38:39], v[38:39], v[46:47]
	v_lshlrev_b32_e32 v47, 16, v53
	v_lshlrev_b32_e32 v46, 16, v52
	v_pk_add_f32 v[36:37], v[36:37], v[44:45]
	v_and_b32_e32 v41, 0xffff0000, v41
	v_and_b32_e32 v40, 0xffff0000, v40
	v_pk_add_f32 v[38:39], v[38:39], v[46:47]
; __device__ __forceinline__ unsigned pk2(float lo, float hi) { return f2bf(lo) | (f2bf(hi) << 16); }
; __device__ __forceinline__ size_t blk_off(int row, int col, int K) { return ((size_t)((row >> 8) * (K >> 6) + (col >> 6)) << 14) + (size_t)(((row & 255) << 6) + (col & 63)); }
; #define POOL_ADD(sgn, VV) do { S[0] += sgn bflo((VV).x); S[1] += sgn bfhi((VV).x); S[2] += sgn bflo((VV).y); S[3] += sgn bfhi((VV).y); S[4] += sgn bflo((VV).z); S[5] += sgn bfhi((VV).z); S[6] += sgn bflo((VV).w); S[7] += sgn bfhi((VV).w); } while (0)
; template <int HW> __device__ __forceinline__ void pool_group(const bf16* PROJ, bf16* CAT, int pbase, int T, int t0, int ch) {
;     ...
;     for (int i = 0; i < NL; ++i) { const int s = t0 - HW + i; const v4u z = {0u, 0u, 0u, 0u}; x[i] = (s >= 0 && s < T) ? *(const v4u*)(PROJ + (size_t)(pbase + s) * INW + 3 * ATTW + 8 * ch) : z; }
;     float S[8];
; #pragma unroll
;     for (int c = 0; c < 8; ++c) S[c] = 0.f;
;     ...
; #pragma unroll
;     for (int i = 0; i < 2 * HW; ++i) POOL_ADD(+, x[i]);
; #pragma unroll
;     for (int k = 0; k < 4; ++k) {
;         if (k > 0) { POOL_ADD(-, x[k - 1]); POOL_ADD(+, x[k - 1 + 2 * HW]); }
;         const int t = t0 + k; const float ic = 1.0f / (float)(min(t + HW, T) - max(t - HW, 0)); const v4u w = x[HW + k];
;         v4u ow; ow.x = pk2(S[0] * ic - bflo(w.x), S[1] * ic - bfhi(w.x)); ow.y = pk2(S[2] * ic - bflo(w.y), S[3] * ic - bfhi(w.y));
;         ow.z = pk2(S[4] * ic - bflo(w.z), S[5] * ic - bfhi(w.z)); ow.w = pk2(S[6] * ic - bflo(w.w), S[7] * ic - bfhi(w.w));
;         *(v4u*)(CAT + blk_off(pbase + t, ATTW + 8 * ch, D)) = ow;
	v_lshlrev_b32_e32 v47, 16, v49
	v_lshlrev_b32_e32 v46, 16, v48
	v_pk_add_f32 v[36:37], v[36:37], v[40:41]
	v_and_b32_e32 v41, 0xffff0000, v53
	v_and_b32_e32 v40, 0xffff0000, v52
	v_lshlrev_b32_e32 v115, 16, v105
	v_lshlrev_b32_e32 v114, 16, v104
	v_pk_add_f32 v[118:119], v[38:39], v[46:47]
	v_pk_add_f32 v[36:37], v[36:37], v[40:41]
	v_and_b32_e32 v41, 0xffff0000, v49
	v_and_b32_e32 v40, 0xffff0000, v48
	v_and_b32_e32 v105, 0xffff0000, v105
	v_and_b32_e32 v104, 0xffff0000, v104
	v_lshlrev_b32_e32 v201, 16, v57
	v_lshlrev_b32_e32 v200, 16, v56
	v_pk_add_f32 v[118:119], v[118:119], v[114:115]
	v_pk_add_f32 v[40:41], v[36:37], v[40:41]
	v_lshlrev_b32_e32 v47, 16, v101
	v_lshlrev_b32_e32 v46, 16, v100
	v_pk_add_f32 v[118:119], v[118:119], v[200:201]
	v_and_b32_e32 v45, 0xffff0000, v57
	v_and_b32_e32 v44, 0xffff0000, v56
	v_pk_add_f32 v[40:41], v[40:41], v[104:105]
	v_lshlrev_b32_e32 v39, 16, v93
	v_lshlrev_b32_e32 v38, 16, v92
	v_pk_add_f32 v[118:119], v[118:119], v[46:47]
	v_and_b32_e32 v57, 0xffff0000, v101
	v_and_b32_e32 v56, 0xffff0000, v100
	v_pk_add_f32 v[40:41], v[40:41], v[44:45]
	v_lshlrev_b32_e32 v123, 16, v125
	v_lshlrev_b32_e32 v122, 16, v124
	v_pk_add_f32 v[118:119], v[118:119], v[38:39]
	v_and_b32_e32 v37, 0xffff0000, v93
	v_and_b32_e32 v36, 0xffff0000, v92
	v_pk_add_f32 v[40:41], v[40:41], v[56:57]
	v_and_b32_e32 v125, 0xffff0000, v125
	v_and_b32_e32 v124, 0xffff0000, v124
	v_lshlrev_b32_e32 v214, 16, v120
	v_lshlrev_b32_e32 v215, 16, v121
	v_pk_add_f32 v[40:41], v[40:41], v[36:37]
	v_pk_add_f32 v[48:49], v[118:119], v[122:123]
	v_and_b32_e32 v120, 0xffff0000, v120
	v_and_b32_e32 v121, 0xffff0000, v121
	v_pk_add_f32 v[40:41], v[40:41], v[124:125]
	v_pk_add_f32 v[48:49], v[48:49], v[214:215]
	v_lshlrev_b32_e32 v53, 16, v117
	v_lshlrev_b32_e32 v52, 16, v116
	v_pk_add_f32 v[40:41], v[40:41], v[120:121]
	v_pk_add_f32 v[48:49], v[48:49], v[52:53]
	v_and_b32_e32 v53, 0xffff0000, v117
	v_and_b32_e32 v52, 0xffff0000, v116
	v_pk_add_f32 v[40:41], v[40:41], v[52:53]
	v_lshlrev_b32_e32 v53, 16, v113
	v_lshlrev_b32_e32 v52, 16, v112
	v_pk_add_f32 v[48:49], v[48:49], v[52:53]
	v_and_b32_e32 v53, 0xffff0000, v113
	v_and_b32_e32 v52, 0xffff0000, v112
	v_pk_add_f32 v[40:41], v[40:41], v[52:53]
	v_pk_fma_f32 v[110:111], v[2:3], v[98:99], v[218:219] op_sel_hi:[0,1,1] neg_lo:[0,0,1] neg_hi:[0,0,1]
	v_pk_fma_f32 v[92:93], v[2:3], v[40:41], v[104:105] op_sel_hi:[0,1,1] neg_lo:[0,0,1] neg_hi:[0,0,1]
	v_pk_fma_f32 v[54:55], v[2:3], v[90:91], v[216:217] op_sel_hi:[0,1,1] neg_lo:[0,0,1] neg_hi:[0,0,1]
	v_pk_fma_f32 v[52:53], v[2:3], v[48:49], v[114:115] op_sel_hi:[0,1,1] neg_lo:[0,0,1] neg_hi:[0,0,1]
	v_bfe_u32 v100, v92, 16, 1
	v_bfe_u32 v104, v110, 16, 1
	v_add3_u32 v104, v110, v104, s15
	v_add3_u32 v92, v92, v100, s15
	v_bfe_u32 v100, v55, 16, 1
	v_bfe_u32 v110, v53, 16, 1
	v_bfe_u32 v2, v93, 16, 1
	v_bfe_u32 v101, v111, 16, 1
	v_add3_u32 v53, v53, v110, s15
	v_add3_u32 v55, v55, v100, s15
	v_add3_u32 v101, v111, v101, s15
	v_add3_u32 v2, v93, v2, s15
	v_lshrrev_b32_e32 v100, 16, v55
	v_lshrrev_b32_e32 v53, 16, v53
	v_and_or_b32 v55, v2, s90, v53
	v_and_or_b32 v53, v101, s90, v100
	v_min_u32_e32 v100, s28, v198
	v_sub_u32_e64 v101, v197, 8 clamp
	v_sub_u32_e32 v100, v100, v101
	v_bfe_u32 v105, v52, 16, 1
	v_cvt_f32_i32_e32 v100, v100
	v_bfe_u32 v93, v54, 16, 1
	v_add3_u32 v52, v52, v105, s15
	v_add3_u32 v54, v54, v93, s15
	v_lshrrev_b32_e32 v52, 16, v52
	v_add_u32_e32 v2, s43, v196
	v_lshrrev_b32_e32 v93, 16, v54
	v_and_or_b32 v54, v92, s90, v52
	v_ashrrev_i32_e32 v92, 4, v2
	v_and_b32_e32 v92, -16, v92
	v_div_scale_f32 v101, s[70:71], v100, v100, 1.0
	v_and_or_b32 v52, v104, s90, v93
	v_add_u32_e32 v92, v92, v173
	v_rcp_f32_e32 v104, v101
	v_ashrrev_i32_e32 v93, 31, v92
	v_lshlrev_b32_e32 v2, 6, v2
	v_and_or_b32 v2, v2, s63, v174
	v_lshlrev_b64 v[92:93], 15, v[92:93]
	v_lshl_add_u64 v[92:93], s[2:3], 0, v[92:93]
	v_lshlrev_b32_e32 v2, 1, v2
	v_lshl_add_u64 v[92:93], v[92:93], 0, v[2:3]
	v_fma_f32 v2, -v101, v104, 1.0
	v_fmac_f32_e32 v104, v2, v104
	v_div_scale_f32 v2, vcc, 1.0, v100, 1.0
	global_store_dwordx4 v[92:93], v[52:55], off
	v_pk_add_f32 v[48:49], v[48:49], v[162:163] neg_lo:[0,1] neg_hi:[0,1]
	v_lshlrev_b32_e32 v93, 16, v109
	v_mul_f32_e32 v52, v2, v104
	v_fma_f32 v53, -v101, v52, v2
	v_fmac_f32_e32 v52, v53, v104
	v_fma_f32 v2, -v101, v52, v2
	v_div_fmas_f32 v2, v2, v104, v52
	v_pk_add_f32 v[52:53], v[90:91], v[166:167] neg_lo:[0,1] neg_hi:[0,1]
	v_lshlrev_b32_e32 v55, 16, v107
	v_lshlrev_b32_e32 v54, 16, v106
	v_lshlrev_b32_e32 v92, 16, v108
	v_pk_add_f32 v[52:53], v[52:53], v[54:55]
	v_pk_add_f32 v[54:55], v[98:99], v[164:165] neg_lo:[0,1] neg_hi:[0,1]
	v_and_b32_e32 v91, 0xffff0000, v107
	v_and_b32_e32 v90, 0xffff0000, v106
	v_pk_add_f32 v[92:93], v[48:49], v[92:93]
	v_pk_add_f32 v[40:41], v[40:41], v[160:161] neg_lo:[0,1] neg_hi:[0,1]
	v_and_b32_e32 v49, 0xffff0000, v109
	v_and_b32_e32 v48, 0xffff0000, v108
	v_div_fixup_f32 v2, v2, v100, 1.0
	v_pk_add_f32 v[54:55], v[54:55], v[90:91]
	v_pk_add_f32 v[40:41], v[40:41], v[48:49]
	v_pk_fma_f32 v[50:51], v[2:3], v[54:55], v[50:51] op_sel_hi:[0,1,1] neg_lo:[0,0,1] neg_hi:[0,0,1]
	v_pk_fma_f32 v[44:45], v[2:3], v[40:41], v[44:45] op_sel_hi:[0,1,1] neg_lo:[0,0,1] neg_hi:[0,0,1]
	v_pk_fma_f32 v[90:91], v[2:3], v[52:53], v[102:103] op_sel_hi:[0,1,1] neg_lo:[0,0,1] neg_hi:[0,0,1]
	v_pk_fma_f32 v[48:49], v[2:3], v[92:93], v[200:201] op_sel_hi:[0,1,1] neg_lo:[0,0,1] neg_hi:[0,0,1]
	v_bfe_u32 v98, v44, 16, 1
	v_bfe_u32 v100, v50, 16, 1
	v_bfe_u32 v2, v45, 16, 1
	v_add3_u32 v100, v50, v100, s15
	v_add3_u32 v44, v44, v98, s15
	v_bfe_u32 v50, v91, 16, 1
	v_bfe_u32 v98, v49, 16, 1
	v_bfe_u32 v99, v51, 16, 1
; __device__ __forceinline__ unsigned pk2(float lo, float hi) { return f2bf(lo) | (f2bf(hi) << 16); }
; __device__ __forceinline__ size_t blk_off(int row, int col, int K) { return ((size_t)((row >> 8) * (K >> 6) + (col >> 6)) << 14) + (size_t)(((row & 255) << 6) + (col & 63)); }
; #define POOL_ADD(sgn, VV) do { S[0] += sgn bflo((VV).x); S[1] += sgn bfhi((VV).x); S[2] += sgn bflo((VV).y); S[3] += sgn bfhi((VV).y); S[4] += sgn bflo((VV).z); S[5] += sgn bfhi((VV).z); S[6] += sgn bflo((VV).w); S[7] += sgn bfhi((VV).w); } while (0)
; template <int HW> __device__ __forceinline__ void pool_group(const bf16* PROJ, bf16* CAT, int pbase, int T, int t0, int ch) {
;     ...
;     for (int i = 0; i < NL; ++i) { const int s = t0 - HW + i; const v4u z = {0u, 0u, 0u, 0u}; x[i] = (s >= 0 && s < T) ? *(const v4u*)(PROJ + (size_t)(pbase + s) * INW + 3 * ATTW + 8 * ch) : z; }
;     float S[8];
; #pragma unroll
;     for (int c = 0; c < 8; ++c) S[c] = 0.f;
;     ...
; #pragma unroll
;     for (int i = 0; i < 2 * HW; ++i) POOL_ADD(+, x[i]);
; #pragma unroll
;     for (int k = 0; k < 4; ++k) {
;         if (k > 0) { POOL_ADD(-, x[k - 1]); POOL_ADD(+, x[k - 1 + 2 * HW]); }
;         const int t = t0 + k; const float ic = 1.0f / (float)(min(t + HW, T) - max(t - HW, 0)); const v4u w = x[HW + k];
;         v4u ow; ow.x = pk2(S[0] * ic - bflo(w.x), S[1] * ic - bfhi(w.x)); ow.y = pk2(S[2] * ic - bflo(w.y), S[3] * ic - bfhi(w.y));
;         ow.z = pk2(S[4] * ic - bflo(w.z), S[5] * ic - bfhi(w.z)); ow.w = pk2(S[6] * ic - bflo(w.w), S[7] * ic - bfhi(w.w));
;         *(v4u*)(CAT + blk_off(pbase + t, ATTW + 8 * ch, D)) = ow;
	v_add3_u32 v2, v45, v2, s15
	v_bfe_u32 v45, v90, 16, 1
	v_add3_u32 v49, v49, v98, s15
	v_add3_u32 v50, v91, v50, s15
	v_add3_u32 v99, v51, v99, s15
	v_bfe_u32 v51, v48, 16, 1
	v_add3_u32 v45, v90, v45, s15
	v_lshrrev_b32_e32 v90, 16, v50
	v_lshrrev_b32_e32 v49, 16, v49
	v_add3_u32 v48, v48, v51, s15
	v_and_or_b32 v51, v2, s90, v49
	v_and_or_b32 v49, v99, s90, v90
	v_min_u32_e32 v90, s28, v147
	v_sub_u32_e64 v91, v151, 8 clamp
	v_sub_u32_e32 v90, v90, v91
	v_cvt_f32_i32_e32 v90, v90
	v_ashrrev_i32_e32 v2, 4, v150
	v_lshrrev_b32_e32 v48, 16, v48
	v_and_b32_e32 v2, -16, v2
	v_div_scale_f32 v91, s[70:71], v90, v90, 1.0
	v_lshrrev_b32_e32 v45, 16, v45
	v_and_or_b32 v50, v44, s90, v48
	v_add_u32_e32 v44, v2, v173
	v_rcp_f32_e32 v98, v91
	v_and_or_b32 v48, v100, s90, v45
	v_ashrrev_i32_e32 v45, 31, v44
	v_lshlrev_b32_e32 v2, 6, v150
	v_and_or_b32 v2, v2, s63, v174
	v_lshlrev_b64 v[44:45], 15, v[44:45]
	v_lshl_add_u64 v[44:45], s[2:3], 0, v[44:45]
	v_lshlrev_b32_e32 v2, 1, v2
	v_lshl_add_u64 v[44:45], v[44:45], 0, v[2:3]
	v_fma_f32 v2, -v91, v98, 1.0
	v_fmac_f32_e32 v98, v2, v98
	v_div_scale_f32 v2, vcc, 1.0, v90, 1.0
	global_store_dwordx4 v[44:45], v[48:51], off
	v_mul_f32_e32 v44, v2, v98
	v_fma_f32 v45, -v91, v44, v2
	v_fmac_f32_e32 v44, v45, v98
	v_fma_f32 v2, -v91, v44, v2
	v_div_fmas_f32 v2, v2, v98, v44
	v_pk_add_f32 v[44:45], v[52:53], v[158:159] neg_lo:[0,1] neg_hi:[0,1]
	v_lshlrev_b32_e32 v49, 16, v87
	v_lshlrev_b32_e32 v48, 16, v86
	v_pk_add_f32 v[44:45], v[44:45], v[48:49]
	v_pk_add_f32 v[48:49], v[54:55], v[156:157] neg_lo:[0,1] neg_hi:[0,1]
	v_and_b32_e32 v51, 0xffff0000, v87
	v_and_b32_e32 v50, 0xffff0000, v86
	v_pk_add_f32 v[52:53], v[92:93], v[154:155] neg_lo:[0,1] neg_hi:[0,1]
	v_lshlrev_b32_e32 v55, 16, v89
	v_lshlrev_b32_e32 v54, 16, v88
	v_div_fixup_f32 v2, v2, v90, 1.0
	v_pk_add_f32 v[48:49], v[48:49], v[50:51]
	v_pk_add_f32 v[52:53], v[52:53], v[54:55]
	v_pk_add_f32 v[40:41], v[40:41], v[152:153] neg_lo:[0,1] neg_hi:[0,1]
	v_and_b32_e32 v55, 0xffff0000, v89
	v_and_b32_e32 v54, 0xffff0000, v88
	v_pk_fma_f32 v[42:43], v[2:3], v[48:49], v[42:43] op_sel_hi:[0,1,1] neg_lo:[0,0,1] neg_hi:[0,0,1]
	v_pk_add_f32 v[54:55], v[40:41], v[54:55]
	v_pk_fma_f32 v[50:51], v[2:3], v[44:45], v[96:97] op_sel_hi:[0,1,1] neg_lo:[0,0,1] neg_hi:[0,0,1]
	v_pk_fma_f32 v[40:41], v[2:3], v[52:53], v[46:47] op_sel_hi:[0,1,1] neg_lo:[0,0,1] neg_hi:[0,0,1]
	v_pk_fma_f32 v[46:47], v[2:3], v[54:55], v[56:57] op_sel_hi:[0,1,1] neg_lo:[0,0,1] neg_hi:[0,0,1]
	v_bfe_u32 v57, v43, 16, 1
	v_bfe_u32 v56, v46, 16, 1
	v_bfe_u32 v86, v42, 16, 1
	v_add3_u32 v57, v43, v57, s15
	v_bfe_u32 v43, v50, 16, 1
	v_add3_u32 v86, v42, v86, s15
	v_add3_u32 v42, v46, v56, s15
	v_bfe_u32 v46, v51, 16, 1
	v_add3_u32 v43, v50, v43, s15
	v_add_u32_e32 v50, 11, v196
	v_add3_u32 v46, v51, v46, s15
	v_min_u32_e32 v50, s28, v50
	v_sub_u32_e64 v51, v149, 8 clamp
	v_sub_u32_e32 v50, v50, v51
	v_bfe_u32 v56, v41, 16, 1
	v_cvt_f32_i32_e32 v50, v50
	v_bfe_u32 v2, v47, 16, 1
	v_add3_u32 v41, v41, v56, s15
	v_add3_u32 v2, v47, v2, s15
	v_bfe_u32 v47, v40, 16, 1
	v_lshrrev_b32_e32 v41, 16, v41
	v_add3_u32 v40, v40, v47, s15
	v_lshrrev_b32_e32 v47, 16, v43
	v_and_or_b32 v43, v2, s90, v41
	v_ashrrev_i32_e32 v2, 4, v148
	v_lshrrev_b32_e32 v46, 16, v46
	v_and_b32_e32 v2, -16, v2
	v_div_scale_f32 v51, s[70:71], v50, v50, 1.0
	v_lshrrev_b32_e32 v40, 16, v40
	v_and_or_b32 v41, v57, s90, v46
	v_add_u32_e32 v46, v2, v173
	v_rcp_f32_e32 v56, v51
	v_and_or_b32 v42, v42, s90, v40
	v_and_or_b32 v40, v86, s90, v47
	v_ashrrev_i32_e32 v47, 31, v46
	v_lshlrev_b32_e32 v2, 6, v148
	v_and_or_b32 v2, v2, s63, v174
	v_lshlrev_b64 v[46:47], 15, v[46:47]
	v_lshl_add_u64 v[46:47], s[2:3], 0, v[46:47]
	v_lshlrev_b32_e32 v2, 1, v2
	v_lshl_add_u64 v[46:47], v[46:47], 0, v[2:3]
	v_fma_f32 v2, -v51, v56, 1.0
	v_fmac_f32_e32 v56, v2, v56
	v_div_scale_f32 v2, vcc, 1.0, v50, 1.0
	global_store_dwordx4 v[46:47], v[40:43], off
	v_and_b32_e32 v47, 0xffff0000, v65
	v_and_b32_e32 v46, 0xffff0000, v64
	v_mul_f32_e32 v40, v2, v56
	v_fma_f32 v41, -v51, v40, v2
	v_fmac_f32_e32 v40, v41, v56
	v_fma_f32 v2, -v51, v40, v2
	v_div_fmas_f32 v2, v2, v56, v40
	v_pk_add_f32 v[40:41], v[44:45], v[84:85] neg_lo:[0,1] neg_hi:[0,1]
	v_lshlrev_b32_e32 v43, 16, v63
	v_lshlrev_b32_e32 v42, 16, v62
	v_pk_add_f32 v[40:41], v[40:41], v[42:43]
	v_pk_add_f32 v[42:43], v[48:49], v[82:83] neg_lo:[0,1] neg_hi:[0,1]
	v_and_b32_e32 v45, 0xffff0000, v63
	v_and_b32_e32 v44, 0xffff0000, v62
	v_div_fixup_f32 v2, v2, v50, 1.0
	v_pk_add_f32 v[42:43], v[42:43], v[44:45]
	v_lshlrev_b32_e32 v45, 16, v65
	v_pk_fma_f32 v[34:35], v[2:3], v[42:43], v[34:35] op_sel_hi:[0,1,1] neg_lo:[0,0,1] neg_hi:[0,0,1]
	v_pk_add_f32 v[42:43], v[52:53], v[60:61] neg_lo:[0,1] neg_hi:[0,1]
	v_lshlrev_b32_e32 v44, 16, v64
	v_pk_add_f32 v[42:43], v[42:43], v[44:45]
	v_pk_add_f32 v[44:45], v[54:55], v[58:59] neg_lo:[0,1] neg_hi:[0,1]
	v_pk_fma_f32 v[40:41], v[2:3], v[40:41], v[94:95] op_sel_hi:[0,1,1] neg_lo:[0,0,1] neg_hi:[0,0,1]
	v_pk_add_f32 v[44:45], v[44:45], v[46:47]
	v_pk_fma_f32 v[38:39], v[2:3], v[42:43], v[38:39] op_sel_hi:[0,1,1] neg_lo:[0,0,1] neg_hi:[0,0,1]
	v_pk_fma_f32 v[36:37], v[2:3], v[44:45], v[36:37] op_sel_hi:[0,1,1] neg_lo:[0,0,1] neg_hi:[0,0,1]
	v_bfe_u32 v2, v37, 16, 1
	v_bfe_u32 v44, v34, 16, 1
	v_add3_u32 v34, v34, v44, s15
	v_add3_u32 v2, v37, v2, s15
	v_bfe_u32 v37, v40, 16, 1
	v_bfe_u32 v44, v39, 16, 1
	v_bfe_u32 v43, v35, 16, 1
	v_add3_u32 v39, v39, v44, s15
	v_add3_u32 v37, v40, v37, s15
	v_add3_u32 v35, v35, v43, s15
	v_bfe_u32 v43, v38, 16, 1
	v_lshrrev_b32_e32 v40, 16, v37
	v_lshrrev_b32_e32 v37, 16, v39
	v_bfe_u32 v42, v36, 16, 1
	v_add3_u32 v38, v38, v43, s15
	v_and_or_b32 v37, v2, s90, v37
	v_ashrrev_i32_e32 v2, 4, v146
	v_add3_u32 v36, v36, v42, s15
	v_lshrrev_b32_e32 v38, 16, v38
	v_and_b32_e32 v2, -16, v2
	v_and_or_b32 v36, v36, s90, v38
	v_add_u32_e32 v38, v2, v173
	v_bfe_u32 v42, v41, 16, 1
	v_ashrrev_i32_e32 v39, 31, v38
	v_lshlrev_b32_e32 v2, 6, v146
	v_add3_u32 v41, v41, v42, s15
	v_and_or_b32 v2, v2, s63, v174
	v_lshlrev_b64 v[38:39], 15, v[38:39]
	v_lshrrev_b32_e32 v41, 16, v41
	v_lshl_add_u64 v[38:39], s[2:3], 0, v[38:39]
	v_lshlrev_b32_e32 v2, 1, v2
	v_and_or_b32 v35, v35, s90, v41
	v_and_or_b32 v34, v34, s90, v40
	v_lshl_add_u64 v[38:39], v[38:39], 0, v[2:3]
	global_store_dwordx4 v[38:39], v[34:37], off
	s_branch .LBB0_356
;     __device__ __forceinline__ void operator()(AccRef acc, const pg8::Unit& u, int wr, int wc, int fr_, int fq_) const {
;     ...
;         const int gpm = pm0 + u.pm, b = batch_of_tile(gpm), grow0 = gpm * 256 + wr * 64 + fr, cl = wc * 32 + 8 * fq;
;         const char* xb = (const char*)(gpm * 256 < NPR ? xp + (size_t)gpm * 256 * D : xs + ((size_t)gpm * 256 - NPR) * D) + (size_t)u.pn * 1024;
; __global__ void __launch_bounds__(NWAVES * 64, 2) fwd(Args a) {
;     ...
;                     const int it = st >> 1, g = wave - 4, pu = pu0 + (it >> 2), tg = 4 * (it & 3) + (lane >> 4), ch = 16 * g + (lane & 15);
.Lxpf:
	v_readlane_b32 s98, v250, 10
	v_readlane_b32 s99, v250, 45
	s_nop 1
	s_lshl_b32 s98, s98, 5
	s_add_i32 s98, s98, s99
	s_and_b32 s99, s97, 7
	s_add_i32 s98, s98, s99
	s_cmp_lt_i32 s98, 64
	s_cselect_b32 s100, s36, s38
	s_cselect_b32 s101, s37, s39
	s_cselect_b32 s99, 0, 64
	s_sub_i32 s98, s98, s99
	s_lshl_b32 s98, s98, 20
	s_lshr_b32 s99, s97, 3
	s_lshl_b32 s99, s99, 10
	s_add_i32 s98, s98, s99
	s_sub_i32 s99, s88, 4
	s_lshl_b32 s99, s99, 3
	s_lshr_b32 vcc_lo, s40, 1
	s_add_i32 s99, s99, vcc_lo
	s_lshl_b32 s99, s99, 15
	s_add_i32 s98, s98, s99
	s_add_u32 s100, s100, s98
	s_addc_u32 s101, s101, 0
	v_and_b32_e32 v240, 63, v0
	v_lshrrev_b32_e32 v241, 4, v240
	v_and_b32_e32 v240, 15, v240
	v_lshlrev_b32_e32 v240, 6, v240
	v_lshl_or_b32 v240, v241, 12, v240
	global_load_dword v241, v240, s[100:101]
	s_add_u32 s100, s100, 0x4000
	s_addc_u32 s101, s101, 0
	global_load_dword v241, v240, s[100:101]
